# merge_split_reduce hand-written: all 32 partial loads in flight (was 4 dependent load/sum/store rounds), same summation order
# speedup vs baseline: 1.0236x; 1.0033x over previous
; __device__ __forceinline__ void xcd_barrier(const XcdBarrier& b) {
;     ...
;     }
;     __syncthreads();
.LBB0_1431:
	s_or_b64 exec, exec, s[36:37]
	v_mov_b32_e32 v36, v226
	s_waitcnt lgkmcnt(0)
	s_barrier
; __device__ __forceinline__ u32x2 pack4(f32x4 v) { u32x2 r; r[0] = cvt_pk(v[0], v[1]); r[1] = cvt_pk(v[2], v[3]); return r; }
; __device__ __forceinline__ void merge_split_reduce(const Params& p) {
;   int tid = threadIdx.x; asm volatile("" : "+v"(tid));
;   const int j = blockIdx.x >> 3, sl = blockIdx.x & 7;
;   int pm, pn; static_tile(36, 8, 256 + j, pm, pn);
;   const float* pt = (const float*)(p.ws + WS_PART) + (size_t)j * 8 * 65536 + sl * 8192;
;   bf16_t* mb = (bf16_t*)(p.ws + WS_MERGEDB) + ((size_t)pm * 256 + sl * 32) * 2048 + pn * 256;
; #pragma unroll
;   for (int it = 0; it < 4; ++it) {
;     const int e = (it * 512 + tid) * 4, rl = e >> 8, cl = e & 255;
;     f32x4 t[8];
; #pragma unroll
;     for (int q = 0; q < 8; ++q) t[q] = *(const f32x4*)(pt + (size_t)q * 65536 + e);
;     f32x4 v = t[0];
; #pragma unroll
;     for (int q = 1; q < 8; ++q) v += t[q];
;     *(u32x2*)(mb + (size_t)rl * 2048 + cl) = pack4(v);
;   }
; }
	v_readlane_b32 s34, v255, 3
	v_readlane_b32 s35, v255, 4
	v_readlane_b32 s36, v253, 52
	v_readlane_b32 s37, v253, 53
	v_lshlrev_b32_e32 v0, 4, v36
	v_lshrrev_b32_e32 v1, 6, v36
	v_lshlrev_b32_e32 v1, 12, v1
	v_and_b32_e32 v2, 63, v36
	v_lshl_add_u32 v1, v2, 3, v1
	s_nop 1
	global_load_dwordx4 v[4:7], v0, s[36:37]
	s_add_u32 s36, s36, 0x40000
	s_addc_u32 s37, s37, 0
	global_load_dwordx4 v[8:11], v0, s[36:37]
	s_add_u32 s36, s36, 0x40000
	s_addc_u32 s37, s37, 0
	global_load_dwordx4 v[12:15], v0, s[36:37]
	s_add_u32 s36, s36, 0x40000
	s_addc_u32 s37, s37, 0
	global_load_dwordx4 v[16:19], v0, s[36:37]
	s_add_u32 s36, s36, 0x40000
	s_addc_u32 s37, s37, 0
	global_load_dwordx4 v[20:23], v0, s[36:37]
	s_add_u32 s36, s36, 0x40000
	s_addc_u32 s37, s37, 0
	global_load_dwordx4 v[24:27], v0, s[36:37]
	s_add_u32 s36, s36, 0x40000
	s_addc_u32 s37, s37, 0
	global_load_dwordx4 v[28:31], v0, s[36:37]
	s_add_u32 s36, s36, 0x40000
	s_addc_u32 s37, s37, 0
	global_load_dwordx4 v[32:35], v0, s[36:37]
	s_sub_u32 s36, s36, 0x1be000
	s_subb_u32 s37, s37, 0
	global_load_dwordx4 v[68:71], v0, s[36:37]
	s_add_u32 s36, s36, 0x40000
	s_addc_u32 s37, s37, 0
	global_load_dwordx4 v[72:75], v0, s[36:37]
	s_add_u32 s36, s36, 0x40000
	s_addc_u32 s37, s37, 0
	global_load_dwordx4 v[76:79], v0, s[36:37]
	s_add_u32 s36, s36, 0x40000
	s_addc_u32 s37, s37, 0
	global_load_dwordx4 v[80:83], v0, s[36:37]
	s_add_u32 s36, s36, 0x40000
	s_addc_u32 s37, s37, 0
	global_load_dwordx4 v[84:87], v0, s[36:37]
	s_add_u32 s36, s36, 0x40000
	s_addc_u32 s37, s37, 0
	global_load_dwordx4 v[88:91], v0, s[36:37]
	s_add_u32 s36, s36, 0x40000
	s_addc_u32 s37, s37, 0
	global_load_dwordx4 v[92:95], v0, s[36:37]
	s_add_u32 s36, s36, 0x40000
	s_addc_u32 s37, s37, 0
	global_load_dwordx4 v[96:99], v0, s[36:37]
	s_sub_u32 s36, s36, 0x1be000
	s_subb_u32 s37, s37, 0
	global_load_dwordx4 v[100:103], v0, s[36:37]
	s_add_u32 s36, s36, 0x40000
	s_addc_u32 s37, s37, 0
	global_load_dwordx4 v[104:107], v0, s[36:37]
	s_add_u32 s36, s36, 0x40000
	s_addc_u32 s37, s37, 0
	global_load_dwordx4 v[108:111], v0, s[36:37]
	s_add_u32 s36, s36, 0x40000
	s_addc_u32 s37, s37, 0
	global_load_dwordx4 v[112:115], v0, s[36:37]
	s_add_u32 s36, s36, 0x40000
	s_addc_u32 s37, s37, 0
	global_load_dwordx4 v[116:119], v0, s[36:37]
	s_add_u32 s36, s36, 0x40000
	s_addc_u32 s37, s37, 0
	global_load_dwordx4 v[120:123], v0, s[36:37]
	s_add_u32 s36, s36, 0x40000
	s_addc_u32 s37, s37, 0
	global_load_dwordx4 v[124:127], v0, s[36:37]
	s_add_u32 s36, s36, 0x40000
	s_addc_u32 s37, s37, 0
	global_load_dwordx4 v[128:131], v0, s[36:37]
	s_sub_u32 s36, s36, 0x1be000
	s_subb_u32 s37, s37, 0
	global_load_dwordx4 v[132:135], v0, s[36:37]
	s_add_u32 s36, s36, 0x40000
	s_addc_u32 s37, s37, 0
	global_load_dwordx4 v[136:139], v0, s[36:37]
	s_add_u32 s36, s36, 0x40000
	s_addc_u32 s37, s37, 0
	global_load_dwordx4 v[140:143], v0, s[36:37]
	s_add_u32 s36, s36, 0x40000
	s_addc_u32 s37, s37, 0
	global_load_dwordx4 v[144:147], v0, s[36:37]
	s_add_u32 s36, s36, 0x40000
	s_addc_u32 s37, s37, 0
	global_load_dwordx4 v[148:151], v0, s[36:37]
	s_add_u32 s36, s36, 0x40000
	s_addc_u32 s37, s37, 0
	global_load_dwordx4 v[152:155], v0, s[36:37]
	s_add_u32 s36, s36, 0x40000
	s_addc_u32 s37, s37, 0
	global_load_dwordx4 v[156:159], v0, s[36:37]
	s_add_u32 s36, s36, 0x40000
	s_addc_u32 s37, s37, 0
	global_load_dwordx4 v[160:163], v0, s[36:37]
	s_waitcnt vmcnt(30)
	v_pk_add_f32 v[6:7], v[6:7], v[10:11]
	v_pk_add_f32 v[4:5], v[4:5], v[8:9]
	s_waitcnt vmcnt(29)
	v_pk_add_f32 v[6:7], v[6:7], v[14:15]
	v_pk_add_f32 v[4:5], v[4:5], v[12:13]
	s_waitcnt vmcnt(28)
	v_pk_add_f32 v[6:7], v[6:7], v[18:19]
	v_pk_add_f32 v[4:5], v[4:5], v[16:17]
	s_waitcnt vmcnt(27)
	v_pk_add_f32 v[6:7], v[6:7], v[22:23]
	v_pk_add_f32 v[4:5], v[4:5], v[20:21]
	s_waitcnt vmcnt(26)
	v_pk_add_f32 v[6:7], v[6:7], v[26:27]
	v_pk_add_f32 v[4:5], v[4:5], v[24:25]
	s_waitcnt vmcnt(25)
	v_pk_add_f32 v[6:7], v[6:7], v[30:31]
	v_pk_add_f32 v[4:5], v[4:5], v[28:29]
	s_waitcnt vmcnt(24)
	v_pk_add_f32 v[6:7], v[6:7], v[34:35]
	v_pk_add_f32 v[4:5], v[4:5], v[32:33]
	v_cvt_pk_bf16_f32 v4, v4, v5
	v_cvt_pk_bf16_f32 v5, v6, v7
	global_store_dwordx2 v1, v[4:5], s[34:35]
	v_add_u32_e32 v1, 0x8000, v1
	s_waitcnt vmcnt(23)
	v_pk_add_f32 v[70:71], v[70:71], v[74:75]
	v_pk_add_f32 v[68:69], v[68:69], v[72:73]
	s_waitcnt vmcnt(22)
	v_pk_add_f32 v[70:71], v[70:71], v[78:79]
	v_pk_add_f32 v[68:69], v[68:69], v[76:77]
	s_waitcnt vmcnt(21)
	v_pk_add_f32 v[70:71], v[70:71], v[82:83]
	v_pk_add_f32 v[68:69], v[68:69], v[80:81]
	s_waitcnt vmcnt(20)
	v_pk_add_f32 v[70:71], v[70:71], v[86:87]
	v_pk_add_f32 v[68:69], v[68:69], v[84:85]
	s_waitcnt vmcnt(19)
	v_pk_add_f32 v[70:71], v[70:71], v[90:91]
	v_pk_add_f32 v[68:69], v[68:69], v[88:89]
	s_waitcnt vmcnt(18)
	v_pk_add_f32 v[70:71], v[70:71], v[94:95]
	v_pk_add_f32 v[68:69], v[68:69], v[92:93]
	s_waitcnt vmcnt(17)
	v_pk_add_f32 v[70:71], v[70:71], v[98:99]
	v_pk_add_f32 v[68:69], v[68:69], v[96:97]
	v_cvt_pk_bf16_f32 v68, v68, v69
	v_cvt_pk_bf16_f32 v69, v70, v71
	global_store_dwordx2 v1, v[68:69], s[34:35]
	v_add_u32_e32 v1, 0x8000, v1
	s_waitcnt vmcnt(16)
	v_pk_add_f32 v[102:103], v[102:103], v[106:107]
	v_pk_add_f32 v[100:101], v[100:101], v[104:105]
	s_waitcnt vmcnt(15)
	v_pk_add_f32 v[102:103], v[102:103], v[110:111]
	v_pk_add_f32 v[100:101], v[100:101], v[108:109]
	s_waitcnt vmcnt(14)
	v_pk_add_f32 v[102:103], v[102:103], v[114:115]
	v_pk_add_f32 v[100:101], v[100:101], v[112:113]
	s_waitcnt vmcnt(13)
	v_pk_add_f32 v[102:103], v[102:103], v[118:119]
	v_pk_add_f32 v[100:101], v[100:101], v[116:117]
	s_waitcnt vmcnt(12)
	v_pk_add_f32 v[102:103], v[102:103], v[122:123]
	v_pk_add_f32 v[100:101], v[100:101], v[120:121]
	s_waitcnt vmcnt(11)
	v_pk_add_f32 v[102:103], v[102:103], v[126:127]
	v_pk_add_f32 v[100:101], v[100:101], v[124:125]
	s_waitcnt vmcnt(10)
	v_pk_add_f32 v[102:103], v[102:103], v[130:131]
	v_pk_add_f32 v[100:101], v[100:101], v[128:129]
	v_cvt_pk_bf16_f32 v100, v100, v101
	v_cvt_pk_bf16_f32 v101, v102, v103
	global_store_dwordx2 v1, v[100:101], s[34:35]
	v_add_u32_e32 v1, 0x8000, v1
	s_waitcnt vmcnt(9)
	v_pk_add_f32 v[134:135], v[134:135], v[138:139]
	v_pk_add_f32 v[132:133], v[132:133], v[136:137]
	s_waitcnt vmcnt(8)
	v_pk_add_f32 v[134:135], v[134:135], v[142:143]
	v_pk_add_f32 v[132:133], v[132:133], v[140:141]
	s_waitcnt vmcnt(7)
	v_pk_add_f32 v[134:135], v[134:135], v[146:147]
	v_pk_add_f32 v[132:133], v[132:133], v[144:145]
	s_waitcnt vmcnt(6)
	v_pk_add_f32 v[134:135], v[134:135], v[150:151]
	v_pk_add_f32 v[132:133], v[132:133], v[148:149]
	s_waitcnt vmcnt(5)
	v_pk_add_f32 v[134:135], v[134:135], v[154:155]
	v_pk_add_f32 v[132:133], v[132:133], v[152:153]
	s_waitcnt vmcnt(4)
	v_pk_add_f32 v[134:135], v[134:135], v[158:159]
	v_pk_add_f32 v[132:133], v[132:133], v[156:157]
	s_waitcnt vmcnt(3)
	v_pk_add_f32 v[134:135], v[134:135], v[162:163]
	v_pk_add_f32 v[132:133], v[132:133], v[160:161]
	v_cvt_pk_bf16_f32 v132, v132, v133
	v_cvt_pk_bf16_f32 v133, v134, v135
	global_store_dwordx2 v1, v[132:133], s[34:35]
